# static priority raise for waves 4-7 during the attention phase (on top of the GEMM-phase raise for waves 0-3)
# baseline (speedup 1.0000x reference)
; #define LAS __attribute__((address_space(3)))
; __device__ __forceinline__ const float* kin(kptr_t p, int i) { return (const float*)(const GAS float*)*(const unsigned long long __attribute__((address_space(4)))*)(p + 8 * i); }
; #define TID() int lane_v_; asm volatile("v_mbcnt_lo_u32_b32 %0, -1, 0\n\tv_mbcnt_hi_u32_b32 %0, -1, %0" : "=v"(lane_v_)); const int tid = wave_s * 64 + lane_v_
; #define PTRS() kptr_t kp = kargs(); unsigned char* ws = kws(kp); (void)ws
; __device__ __forceinline__ void attn_phase(LAS unsigned char* lds, const bf16_t* QKVZ, const float* sinks, bf16_t* OG, int G, int bid, int tid) {
;     const int wave = __builtin_amdgcn_readfirstlane(tid >> 6), lane = tid & 63, fr = lane & 15, fq = lane >> 4;
;     constexpr int KP = 144, VP = 528;
;     LAS unsigned char* Kl = lds; LAS unsigned char* Vt = lds + 256 * KP;
;     u32x4 pkv[4], pvv[4];
;     ...
;     if (bid < 1024) ATT_LOAD(bid);
; __global__ void __launch_bounds__(NTHR, 2) hybrid_fwd(Args a) {
;     ...
;     if (IN(2)) for (int rep_ = 0; rep_ < REPS(2); ++rep_) { TID(); PTRS(); attn_phase(lds, QKVZ, kin(kp, I_ASINK), S1, G, bid, tid); }
.LBB0_224:
	v_readlane_b32 s2, v254, 1
	v_readlane_b32 s3, v254, 2
	s_cmp_lt_i32 s2, 3
	s_cselect_b64 s[2:3], -1, 0
	s_and_b64 s[2:3], s[2:3], s[0:1]
	s_andn2_b64 vcc, exec, s[2:3]
	s_cbranch_vccnz .LBB0_248
	v_readlane_b32 s98, v254, 3
	s_cmp_ge_u32 s98, 0x100
	s_cbranch_scc0 .Lmy_prio_2
	s_setprio 1
.Lmy_prio_2:
	v_mbcnt_lo_u32_b32 v34, -1, 0
	v_mbcnt_hi_u32_b32 v34, -1, v34
	s_cmpk_gt_i32 s84, 0x3ff
	v_add_u32_e32 v28, s52, v34
	s_mov_b64 s[6:7], s[82:83]
	v_readfirstlane_b32 s12, v28
	s_cbranch_scc1 .LBB0_248
	s_load_dwordx2 s[0:1], s[6:7], 0xc8
	s_lshl_b32 s16, s84, 5
	s_waitcnt lgkmcnt(0)
	s_and_b32 s10, s16, 0xf80
	s_and_b32 s13, s16, 0xfffff000
	s_addk_i32 s10, 0xff80
	s_add_u32 s4, s0, 0x8000000
	s_addc_u32 s5, s1, 0
	s_lshl_b32 s8, s84, 7
	s_and_b32 s8, s8, 0x180
	v_lshlrev_b32_e32 v0, 3, v34
	v_mov_b32_e32 v73, 0
	s_add_u32 s8, s4, s8
	v_and_b32_e32 v0, 56, v0
	v_ashrrev_i32_e32 v77, 3, v28
	v_mov_b32_e32 v6, v73
	v_mov_b32_e32 v7, v73
	s_addc_u32 s9, s5, 0
	v_lshlrev_b32_e32 v72, 1, v0
	v_add_u32_e32 v12, s10, v77
	v_mov_b32_e32 v4, v73
	v_mov_b32_e32 v5, v73
	v_mov_b64_e32 v[10:11], v[6:7]
	v_lshl_add_u64 v[32:33], s[8:9], 0, v[72:73]
	v_cmp_lt_i32_e32 vcc, -1, v12
	v_mov_b32_e32 v0, v73
	v_mov_b32_e32 v1, v73
	v_mov_b32_e32 v2, v73
	v_mov_b32_e32 v3, v73
	v_mov_b64_e32 v[8:9], v[4:5]
	s_and_saveexec_b64 s[8:9], vcc
	s_cbranch_execz .LBB0_228
	v_add_u32_e32 v0, s13, v12
	s_movk_i32 s11, 0x1400
	v_mad_i64_i32 v[12:13], s[14:15], v0, s11, v[32:33]
	global_load_dwordx4 v[8:11], v[12:13], off offset:2048
	global_load_dwordx4 v[0:3], v[12:13], off offset:2560

; __device__ __forceinline__ unsigned xb_ld(unsigned* p)              { return __hip_atomic_load(p, __ATOMIC_RELAXED, __HIP_MEMORY_SCOPE_AGENT); }
; __device__ __forceinline__ unsigned xb_add(unsigned* p, unsigned v) { return __hip_atomic_fetch_add(p, v, __ATOMIC_RELAXED, __HIP_MEMORY_SCOPE_AGENT); }
; __device__ __forceinline__ void xcd_barrier_complete(unsigned* bar, unsigned x, unsigned& nloc, unsigned& nx) {
;     const unsigned G = gridDim.x * gridDim.y * gridDim.z;
;     unsigned sum, cnt, mine, sp = 0u;
;     for (;;) {
;         sum = 0u; cnt = 0u; mine = 0u;
; #pragma unroll
;         for (unsigned j = 0; j < 16; ++j) { const unsigned c = xb_ld(&bar[XB_XCNT(j)]); sum += c; cnt += (c > 0u) ? 1u : 0u; mine = (j == x) ? c : mine; }
; __device__ __forceinline__ void xcd_barrier(const XcdBarrier& b, const int tid_) {
;     asm volatile("s_waitcnt vmcnt(0)" ::: "memory");
;     __syncthreads();
;     if (tid_ == 0) {
;         unsigned* bar = b.bar;
;         __builtin_amdgcn_s_waitcnt(0);
;         unsigned nloc = b.st[0], nx = b.st[1];
;         if (nloc == 0u) { xcd_barrier_complete(bar, b.x, nloc, nx); b.st[0] = nloc; b.st[1] = nx; }
;         const unsigned old = xb_add(&bar[XB_XSUB(b.x)], 1u);
.LBB0_248:
	s_setprio 0
	v_readlane_b32 s0, v254, 1
	v_readlane_b32 s1, v254, 2
	s_cmp_gt_i32 s1, 3
	s_cselect_b64 s[0:1], -1, 0
	s_and_b64 s[2:3], s[2:3], s[0:1]
	s_andn2_b64 vcc, exec, s[2:3]
	s_cbranch_vccnz .LBB0_302
	s_mov_b64 s[4:5], s[82:83]
	v_mbcnt_lo_u32_b32 v0, -1, 0
	v_mbcnt_hi_u32_b32 v0, -1, v0
	s_getreg_b32 s6, hwreg(HW_REG_XCC_ID, 0, 4)
	s_waitcnt vmcnt(0)
	v_sub_u32_e32 v0, 0, v0
	v_cmp_eq_u32_e32 vcc, s52, v0
	s_waitcnt vmcnt(0) lgkmcnt(0)
	s_barrier
	s_and_saveexec_b64 s[2:3], vcc
	s_cbranch_execz .LBB0_301
	s_add_i32 s7, 0, 0x23fc0
	v_mov_b32_e32 v0, s7
	s_load_dwordx2 s[4:5], s[4:5], 0xc8
	s_waitcnt vmcnt(0) expcnt(0) lgkmcnt(0)
	ds_read_b32 v2, v0
	s_add_i32 s7, 0, 0x23fc4
	v_mov_b32_e32 v0, s7
	ds_read_b32 v0, v0
	s_and_b32 s33, s6, 15
	s_waitcnt lgkmcnt(1)
	v_cmp_ne_u32_e32 vcc, 0, v2
	s_cbranch_vccnz .LBB0_265
	s_load_dword s6, s[82:83], 0xe0
	s_mov_b32 s49, 1
	v_mov_b32_e32 v16, 0
	s_waitcnt lgkmcnt(0)
	s_mul_i32 s48, s55, s6
	s_add_u32 s6, s4, 0x1900200
	s_addc_u32 s7, s5, 0
	s_add_u32 s8, s4, 0x1900400
	s_addc_u32 s9, s5, 0
	s_add_u32 s10, s4, 0x1900500
	s_addc_u32 s11, s5, 0
	s_add_u32 s12, s4, 0x1900600
	s_addc_u32 s13, s5, 0
	s_add_u32 s14, s4, 0x1900700
	s_addc_u32 s15, s5, 0
	s_add_u32 s16, s4, 0x1900800
	s_addc_u32 s17, s5, 0
	s_add_u32 s18, s4, 0x1900900
	s_addc_u32 s19, s5, 0
	s_add_u32 s20, s4, 0x1900a00
	s_addc_u32 s21, s5, 0
	s_add_u32 s22, s4, 0x1900b00
	s_addc_u32 s23, s5, 0
	s_add_u32 s24, s4, 0x1900c00
	s_addc_u32 s25, s5, 0
	s_add_u32 s26, s4, 0x1900d00
	s_addc_u32 s27, s5, 0
	s_add_u32 s28, s4, 0x1900e00
	s_addc_u32 s29, s5, 0
	s_add_u32 s30, s4, 0x1900f00
	s_addc_u32 s31, s5, 0
	s_add_u32 s34, s4, 0x1901000
	s_addc_u32 s35, s5, 0
	s_add_u32 s36, s4, 0x1901100
	s_addc_u32 s37, s5, 0
	s_add_u32 s38, s4, 0x1901200
	s_addc_u32 s39, s5, 0
	s_add_u32 s40, s4, 0x1901300
	s_mul_i32 s48, s48, s54
	s_addc_u32 s41, s5, 0
	s_branch .LBB0_253
